# GQA attention loop: K/V tile loads use SGPR base + 32-bit lane offset (SALU adds) instead of per-tile 64-bit VALU address math; on top of v31
# speedup vs baseline: 1.0035x; 1.0035x over previous
; __device__ __forceinline__ void finishSM(f32x16& p0, f32x16& p1, float alpha, float& l_reg, bf16x8& pa0, bf16x8& pa1, bf16x8& pa2, bf16x8& pa3) {
; #pragma unroll
;   for (int r = 0; r < 16; ++r) p1[r] = __builtin_amdgcn_exp2f(p1[r]);
;   float ps = 0;
; #pragma unroll
;   for (int r = 0; r < 16; ++r) ps += p0[r];
; #pragma unroll
;   for (int r = 0; r < 16; ++r) ps += p1[r];
;   { auto rr = __builtin_amdgcn_permlane32_swap(__float_as_uint(ps), __float_as_uint(ps), false, false);
;     ps = __uint_as_float(rr[0]) + __uint_as_float(rr[1]); }
;   l_reg = l_reg * alpha + ps;
;     ...
;   PK4(p0, 0, pa0); PK4(p0, 8, pa1); PK4(p1, 0, pa2); PK4(p1, 8, pa3);
;     ...
; }
; template <int DK, int NPARK>
; __device__ __forceinline__ void qkt(f32x16& p0, f32x16& p1, const char* Ks, const bf16x8* qr, const char* qpark, int r32, int hi) {
;   p0 = f32x16{}; p1 = f32x16{};
; #pragma unroll
;   for (int d0 = 0; d0 < DK / 16; ++d0) { const int cb = (d0 * 16 + hi * 8) * 2;
;     bf16x8 b0 = *reinterpret_cast<const bf16x8*>(Ks + kswz<DK>(r32, cb));
;     bf16x8 b1 = *reinterpret_cast<const bf16x8*>(Ks + kswz<DK>(32 + r32, cb));
;     bf16x8 q;
;     if constexpr (NPARK > 0) { if (d0 >= DK / 16 - NPARK) q = *reinterpret_cast<const bf16x8*>(qpark + (d0 - (DK / 16 - NPARK)) * 1024); else q = qr[d0]; } else q = qr[d0];
;     p0 = __builtin_amdgcn_mfma_f32_32x32x16_bf16(b0, q, p0, 0, 0, 0);
;     p1 = __builtin_amdgcn_mfma_f32_32x32x16_bf16(b1, q, p1, 0, 0, 0); }
; }
; __device__ __forceinline__ int v_st(int k, int c) { const int kk = (k & ~0xC) | ((k & 4) << 1) | ((k & 8) >> 1); return ((kk >> 3) * 4 + (c >> 5)) * 512 + ((kk & 7) * 32 + (c & 31)) * 2; }
; __device__ __forceinline__ int v_rd_base(int lane) { return ((lane & 3) << 3) | (((lane >> 2) & 3) << 6) | (((lane >> 4) & 1) << 5) | (((lane >> 5) & 1) << 8); }
; template <int OFF> __device__ __forceinline__ s16x4 tr_read(int vb) {
;   s16x4 r; asm volatile("ds_read_b64_tr_b16 %0, %1 offset:%2" : "=&v"(r) : "v"(vb), "i"(OFF) : "memory"); return r;
; }
; template <int D0> __device__ __forceinline__ void pv_one(f32x16& od, int vb, bf16x8 pa0, bf16x8 pa1, bf16x8 pa2, bf16x8 pa3) {
;   const s16x4 l0 = tr_read<v_rd_off(D0, 0, 0)>(vb), h0 = tr_read<v_rd_off(D0, 0, 1)>(vb), l1 = tr_read<v_rd_off(D0, 1, 0)>(vb), h1 = tr_read<v_rd_off(D0, 1, 1)>(vb);
.LBB0_924:
	ds_read_b128 v[64:67], v161 offset:49152
	ds_read_b128 v[68:71], v161 offset:57344
	ds_read_b128 v[194:197], v170 offset:49152
	ds_read_b128 v[198:201], v170 offset:57344
	v_add_f32_e32 v144, 0, v145
	v_add_f32_e32 v144, v187, v144
	s_waitcnt lgkmcnt(3)
	v_mfma_f32_32x32x16_bf16 v[80:95], v[64:67], v[112:115], 0
	v_add_f32_e32 v144, v146, v144
	v_add_f32_e32 v144, v188, v144
	v_add_f32_e32 v144, v186, v144
	v_add_f32_e32 v144, v189, v144
	v_add_f32_e32 v144, v147, v144
	v_add_f32_e32 v144, v185, v144
	v_add_f32_e32 v144, v157, v144
	s_waitcnt lgkmcnt(2)
	v_mfma_f32_32x32x16_bf16 v[64:79], v[68:71], v[112:115], 0
	v_add_f32_e32 v144, v181, v144
	v_add_f32_e32 v144, v179, v144
	v_add_f32_e32 v144, v182, v144
	v_exp_f32_e32 v142, v142
	v_add_f32_e32 v144, v154, v144
	v_exp_f32_e32 v143, v143
	v_add_f32_e32 v144, v155, v144
	s_waitcnt lgkmcnt(1)
	v_mfma_f32_32x32x16_bf16 v[80:95], v[194:197], v[108:111], v[80:95]
	v_exp_f32_e32 v140, v140
	v_add_f32_e32 v144, v156, v144
	v_exp_f32_e32 v141, v141
	v_add_f32_e32 v144, v180, v144
	v_exp_f32_e32 v136, v136
	v_add_f32_e32 v144, v142, v144
	v_exp_f32_e32 v137, v137
	s_waitcnt lgkmcnt(0)
	v_mfma_f32_32x32x16_bf16 v[64:79], v[198:201], v[108:111], v[64:79]
	ds_read_b128 v[194:197], v169 offset:49152
	ds_read_b128 v[198:201], v169 offset:57344
	v_add_f32_e32 v144, v143, v144
	v_exp_f32_e32 v132, v132
	v_add_f32_e32 v144, v140, v144
	v_exp_f32_e32 v133, v133
	v_add_f32_e32 v144, v141, v144
	v_exp_f32_e32 v130, v130
	s_waitcnt lgkmcnt(1)
	v_mfma_f32_32x32x16_bf16 v[80:95], v[194:197], v[120:123], v[80:95]
	v_add_f32_e32 v144, v136, v144
	v_exp_f32_e32 v131, v131
	v_add_f32_e32 v144, v137, v144
	v_exp_f32_e32 v138, v138
	v_add_f32_e32 v144, v132, v144
	v_exp_f32_e32 v139, v139
	v_add_f32_e32 v144, v133, v144
	s_waitcnt lgkmcnt(0)
	v_mfma_f32_32x32x16_bf16 v[64:79], v[198:201], v[120:123], v[64:79]
	ds_read_b128 v[194:197], v168 offset:49152
	ds_read_b128 v[198:201], v168 offset:57344
	v_exp_f32_e32 v134, v134
	v_add_f32_e32 v144, v130, v144
	v_exp_f32_e32 v135, v135
	v_add_f32_e32 v144, v131, v144
	v_exp_f32_e32 v128, v128
	v_add_f32_e32 v144, v138, v144
	s_waitcnt lgkmcnt(1)
	v_mfma_f32_32x32x16_bf16 v[80:95], v[194:197], v[124:127], v[80:95]
	v_exp_f32_e32 v129, v129
	v_add_f32_e32 v144, v139, v144
	v_add_f32_e32 v144, v134, v144
	v_add_f32_e32 v144, v135, v144
	v_add_f32_e32 v144, v128, v144
	v_add_f32_e32 v175, v129, v144
	v_mov_b32_e32 v176, v175
	s_waitcnt lgkmcnt(0)
	v_mfma_f32_32x32x16_bf16 v[64:79], v[198:201], v[124:127], v[64:79]
	ds_read_b128 v[194:197], v167 offset:49152
	ds_read_b128 v[198:201], v167 offset:57344
	v_permlane32_swap_b32_e32 v175, v176
	s_waitcnt lgkmcnt(1)
	v_mfma_f32_32x32x16_bf16 v[80:95], v[194:197], v[116:119], v[80:95]
	s_waitcnt lgkmcnt(0)
	v_mfma_f32_32x32x16_bf16 v[64:79], v[198:201], v[116:119], v[64:79]
	ds_read_b128 v[194:197], v166 offset:49152
	ds_read_b128 v[198:201], v166 offset:57344
	s_waitcnt lgkmcnt(1)
	v_mfma_f32_32x32x16_bf16 v[80:95], v[194:197], v[104:107], v[80:95]
	s_waitcnt lgkmcnt(0)
	v_mfma_f32_32x32x16_bf16 v[64:79], v[198:201], v[104:107], v[64:79]
	ds_read_b128 v[194:197], v172 offset:49152
	ds_read_b128 v[198:201], v172 offset:57344
	s_waitcnt lgkmcnt(1)
	v_mfma_f32_32x32x16_bf16 v[80:95], v[194:197], v[100:103], v[80:95]
	s_waitcnt lgkmcnt(0)
	v_mfma_f32_32x32x16_bf16 v[64:79], v[198:201], v[100:103], v[64:79]
	ds_read_b128 v[194:197], v171 offset:49152
	ds_read_b128 v[198:201], v171 offset:57344
	v_cvt_pk_bf16_f32 v144, v145, v187
	v_cvt_pk_bf16_f32 v145, v146, v188
	v_cvt_pk_bf16_f32 v146, v186, v189
	v_cvt_pk_bf16_f32 v147, v147, v185
	v_cvt_pk_bf16_f32 v184, v157, v181
	v_cvt_pk_bf16_f32 v185, v179, v182
	s_waitcnt lgkmcnt(1)
	v_mfma_f32_32x32x16_bf16 v[80:95], v[194:197], v[96:99], v[80:95]
	v_permlane32_swap_b32_e32 v144, v146
	v_cvt_pk_bf16_f32 v186, v154, v155
	v_cvt_pk_bf16_f32 v187, v156, v180
	v_cvt_pk_bf16_f32 v180, v142, v143
	v_cvt_pk_bf16_f32 v181, v140, v141
	v_cvt_pk_bf16_f32 v182, v136, v137
	s_waitcnt lgkmcnt(0)
	v_mfma_f32_32x32x16_bf16 v[64:79], v[198:201], v[96:99], v[64:79]
	v_cvt_pk_bf16_f32 v183, v132, v133
	v_cvt_pk_bf16_f32 v188, v130, v131
	v_cvt_pk_bf16_f32 v189, v138, v139
	v_cvt_pk_bf16_f32 v190, v134, v135
	v_cvt_pk_bf16_f32 v191, v128, v129
	v_permlane32_swap_b32_e32 v145, v147
	v_permlane32_swap_b32_e32 v184, v186
	v_permlane32_swap_b32_e32 v185, v187
	v_permlane32_swap_b32_e32 v180, v182
	v_permlane32_swap_b32_e32 v181, v183
	v_permlane32_swap_b32_e32 v188, v190
	v_permlane32_swap_b32_e32 v189, v191
	s_add_u32 s46, s10, s0
	s_addc_u32 s47, s11, 0
	s_add_u32 s48, s10, s67
	s_addc_u32 s49, s11, 0
	global_load_dwordx4 v[128:131], v192, s[46:47]
	global_load_dwordx4 v[132:135], v152, s[46:47]
	global_load_dwordx4 v[136:139], v192, s[48:49]
	global_load_dwordx4 v[140:143], v152, s[48:49]
	ds_read_b64_tr_b16 v[194:195], v160 offset:0
	ds_read_b64_tr_b16 v[196:197], v160 offset:0x800
	ds_read_b64_tr_b16 v[198:199], v160 offset:0x1000
	ds_read_b64_tr_b16 v[200:201], v160 offset:0x1800
	ds_read_b64_tr_b16 v[202:203], v160 offset:0x2000
	ds_read_b64_tr_b16 v[204:205], v160 offset:0x2800
	ds_read_b64_tr_b16 v[206:207], v160 offset:0x3000
	ds_read_b64_tr_b16 v[208:209], v160 offset:0x3800
	s_waitcnt lgkmcnt(0)
	s_nop 0
	v_mfma_f32_32x32x16_bf16 v[0:15], v[144:147], v[194:197], v[0:15]
	ds_read_b64_tr_b16 v[194:195], v160 offset:0x200
	ds_read_b64_tr_b16 v[196:197], v160 offset:0xa00
	v_mfma_f32_32x32x16_bf16 v[0:15], v[184:187], v[198:201], v[0:15]
	ds_read_b64_tr_b16 v[198:199], v160 offset:0x1200
	ds_read_b64_tr_b16 v[200:201], v160 offset:0x1a00
	v_mfma_f32_32x32x16_bf16 v[0:15], v[180:183], v[202:205], v[0:15]
	ds_read_b64_tr_b16 v[202:203], v160 offset:0x2200
	ds_read_b64_tr_b16 v[204:205], v160 offset:0x2a00
	v_mfma_f32_32x32x16_bf16 v[0:15], v[188:191], v[206:209], v[0:15]
	ds_read_b64_tr_b16 v[206:207], v160 offset:0x3200
	ds_read_b64_tr_b16 v[208:209], v160 offset:0x3a00
	s_waitcnt lgkmcnt(0)
; #define SBAR() __builtin_amdgcn_sched_barrier(0)
; template <int DK>
; __device__ __forceinline__ void partialSM(f32x16& p0, f32x16& p1, float& m_reg, float& mn, float& alpha) {
;   constexpr float SCALE = Cst<DK>::SCALE, C = SCALE * 1.4426950408889634f;
;   float pmax = p0[0];
; #pragma unroll
;   for (int r = 1; r < 16; ++r) pmax = fmaxf(pmax, p0[r]);
; #pragma unroll
;   for (int r = 0; r < 16; ++r) pmax = fmaxf(pmax, p1[r]);
;   { auto rr = __builtin_amdgcn_permlane32_swap(__float_as_uint(pmax), __float_as_uint(pmax), false, false);
;     pmax = fmaxf(__uint_as_float(rr[0]), __uint_as_float(rr[1])); }
;   if (__builtin_expect(__all(pmax - m_reg <= THR / SCALE), 1)) { mn = m_reg; alpha = 1.f; }
;   else { mn = fmaxf(m_reg, pmax); alpha = __builtin_amdgcn_exp2f((m_reg - mn) * C); m_reg = mn; }
; template <int D0> __device__ __forceinline__ void pv_one(f32x16& od, int vb, bf16x8 pa0, bf16x8 pa1, bf16x8 pa2, bf16x8 pa3) {
;   const s16x4 l0 = tr_read<v_rd_off(D0, 0, 0)>(vb), h0 = tr_read<v_rd_off(D0, 0, 1)>(vb), l1 = tr_read<v_rd_off(D0, 1, 0)>(vb), h1 = tr_read<v_rd_off(D0, 1, 1)>(vb);
;   const s16x4 l2 = tr_read<v_rd_off(D0, 2, 0)>(vb), h2 = tr_read<v_rd_off(D0, 2, 1)>(vb), l3 = tr_read<v_rd_off(D0, 3, 0)>(vb), h3 = tr_read<v_rd_off(D0, 3, 1)>(vb);
;   asm volatile("s_waitcnt lgkmcnt(0)" ::: "memory"); SBAR();
;     ...
;   od = __builtin_amdgcn_mfma_f32_32x32x16_bf16(pa0, PK(l0, h0), od, 0, 0, 0);
;   od = __builtin_amdgcn_mfma_f32_32x32x16_bf16(pa1, PK(l1, h1), od, 0, 0, 0);
;   od = __builtin_amdgcn_mfma_f32_32x32x16_bf16(pa2, PK(l2, h2), od, 0, 0, 0);
;   od = __builtin_amdgcn_mfma_f32_32x32x16_bf16(pa3, PK(l3, h3), od, 0, 0, 0);
;     ...
; }
; __device__ __forceinline__ void pv_d0(f32x16* o, int vb, bf16x8 pa0, bf16x8 pa1, bf16x8 pa2, bf16x8 pa3) {
;   pv_one<0>(o[0], vb, pa0, pa1, pa2, pa3); pv_one<1>(o[1], vb, pa0, pa1, pa2, pa3); pv_one<2>(o[2], vb, pa0, pa1, pa2, pa3); pv_one<3>(o[3], vb, pa0, pa1, pa2, pa3);
	v_mfma_f32_32x32x16_bf16 v[48:63], v[144:147], v[194:197], v[48:63]
	ds_read_b64_tr_b16 v[194:195], v160 offset:0x400
	ds_read_b64_tr_b16 v[196:197], v160 offset:0xc00
	v_mfma_f32_32x32x16_bf16 v[48:63], v[184:187], v[198:201], v[48:63]
	ds_read_b64_tr_b16 v[198:199], v160 offset:0x1400
	ds_read_b64_tr_b16 v[200:201], v160 offset:0x1c00
	v_mfma_f32_32x32x16_bf16 v[48:63], v[180:183], v[202:205], v[48:63]
	ds_read_b64_tr_b16 v[202:203], v160 offset:0x2400
	ds_read_b64_tr_b16 v[204:205], v160 offset:0x2c00
	v_mfma_f32_32x32x16_bf16 v[48:63], v[188:191], v[206:209], v[48:63]
	ds_read_b64_tr_b16 v[206:207], v160 offset:0x3400
	ds_read_b64_tr_b16 v[208:209], v160 offset:0x3c00
	s_waitcnt lgkmcnt(0)
	v_mfma_f32_32x32x16_bf16 v[32:47], v[144:147], v[194:197], v[32:47]
	ds_read_b64_tr_b16 v[194:195], v160 offset:0x600
	ds_read_b64_tr_b16 v[196:197], v160 offset:0xe00
	v_mfma_f32_32x32x16_bf16 v[32:47], v[184:187], v[198:201], v[32:47]
	ds_read_b64_tr_b16 v[198:199], v160 offset:0x1600
	ds_read_b64_tr_b16 v[200:201], v160 offset:0x1e00
	v_mfma_f32_32x32x16_bf16 v[32:47], v[180:183], v[202:205], v[32:47]
	ds_read_b64_tr_b16 v[202:203], v160 offset:0x2600
	ds_read_b64_tr_b16 v[204:205], v160 offset:0x2e00
	v_mfma_f32_32x32x16_bf16 v[32:47], v[188:191], v[206:209], v[32:47]
	ds_read_b64_tr_b16 v[206:207], v160 offset:0x3600
	ds_read_b64_tr_b16 v[208:209], v160 offset:0x3e00
	s_waitcnt lgkmcnt(0)
	v_mfma_f32_32x32x16_bf16 v[16:31], v[144:147], v[194:197], v[16:31]
	v_max_f32_e32 v144, v81, v81
	v_max_f32_e32 v145, v80, v80
	v_max_f32_e32 v144, v145, v144
	v_max3_f32 v144, v144, v82, v83
	v_max3_f32 v144, v144, v84, v85
	v_max3_f32 v144, v144, v86, v87
	v_max3_f32 v144, v144, v88, v89
	v_max3_f32 v144, v144, v90, v91
	v_max3_f32 v144, v144, v92, v93
	v_mfma_f32_32x32x16_bf16 v[16:31], v[184:187], v[198:201], v[16:31]
	v_max3_f32 v144, v144, v94, v95
	v_max3_f32 v144, v144, v64, v65
	v_max3_f32 v144, v144, v66, v67
	v_max3_f32 v144, v144, v68, v69
	v_max3_f32 v144, v144, v70, v71
	v_max3_f32 v144, v144, v72, v73
	v_max3_f32 v144, v144, v74, v75
	v_max3_f32 v144, v144, v76, v77
	v_mfma_f32_32x32x16_bf16 v[16:31], v[180:183], v[202:205], v[16:31]
	v_max3_f32 v144, v144, v78, v79
	v_mov_b32_e32 v145, v144
	s_nop 1
	v_permlane32_swap_b32_e32 v144, v145
	v_max_f32_e32 v145, v145, v145
	v_max_f32_e32 v144, v144, v144
	v_max_f32_e32 v144, v144, v145
	v_sub_f32_e32 v145, v144, v174
	v_cmp_ge_f32_e32 vcc, s1, v145
	v_max_f32_e32 v145, v174, v174
	v_max_f32_e32 v144, v145, v144
	v_mfma_f32_32x32x16_bf16 v[16:31], v[188:191], v[206:209], v[16:31]
	v_sub_f32_e32 v145, v174, v144
	v_mul_f32_e32 v145, 0x3e0293ee, v145
	v_exp_f32_e32 v145, v145
	s_cmp_eq_u64 vcc, exec
	s_cselect_b64 s[8:9], -1, 0
	s_barrier
	s_waitcnt vmcnt(0)
	v_cndmask_b32_e64 v177, v145, 1.0, s[8:9]
	v_cmp_gt_f32_e32 vcc, 1.0, v177
	s_waitcnt vmcnt(3)
	ds_write_b128 v164, v[128:131]
	s_waitcnt vmcnt(2)
	ds_write_b128 v165, v[132:135]
	s_waitcnt vmcnt(1)
	ds_write_b128 v162, v[136:139] offset:32768
	s_waitcnt vmcnt(0)
	ds_write_b128 v163, v[140:143] offset:32768
	s_cbranch_vccz .LBB0_928
	s_and_saveexec_b64 s[12:13], s[6:7]
	ds_write_b32 v151, v177 offset:128
	s_or_b64 exec, exec, s[12:13]
	s_waitcnt lgkmcnt(0)
	v_add_u32_e32 v140, s95, v150
	ds_read_b128 v[128:131], v140 offset:224
	ds_read_b128 v[132:135], v140 offset:192
	ds_read_b128 v[136:139], v140 offset:160
	ds_read_b128 v[140:143], v140 offset:128
	s_waitcnt lgkmcnt(3)
	v_pk_mul_f32 v[12:13], v[12:13], v[128:129]
	s_waitcnt lgkmcnt(2)
	v_pk_mul_f32 v[8:9], v[8:9], v[132:133]
	s_waitcnt lgkmcnt(1)
	v_pk_mul_f32 v[4:5], v[4:5], v[136:137]
	v_pk_mul_f32 v[14:15], v[14:15], v[130:131]
	v_pk_mul_f32 v[10:11], v[10:11], v[134:135]
	v_pk_mul_f32 v[6:7], v[6:7], v[138:139]
	s_waitcnt lgkmcnt(0)
	v_pk_mul_f32 v[2:3], v[2:3], v[142:143]
	v_pk_mul_f32 v[0:1], v[0:1], v[140:141]
	v_pk_mul_f32 v[60:61], v[60:61], v[128:129]
	v_pk_mul_f32 v[56:57], v[56:57], v[132:133]
	v_pk_mul_f32 v[52:53], v[52:53], v[136:137]
	v_pk_mul_f32 v[62:63], v[62:63], v[130:131]
	v_pk_mul_f32 v[58:59], v[58:59], v[134:135]
	v_pk_mul_f32 v[54:55], v[54:55], v[138:139]
	v_pk_mul_f32 v[50:51], v[50:51], v[142:143]
	v_pk_mul_f32 v[48:49], v[48:49], v[140:141]
	v_pk_mul_f32 v[44:45], v[44:45], v[128:129]
	v_pk_mul_f32 v[40:41], v[40:41], v[132:133]
	v_pk_mul_f32 v[36:37], v[36:37], v[136:137]
	v_pk_mul_f32 v[46:47], v[46:47], v[130:131]
	v_pk_mul_f32 v[42:43], v[42:43], v[134:135]
	v_pk_mul_f32 v[38:39], v[38:39], v[138:139]
	v_pk_mul_f32 v[34:35], v[34:35], v[142:143]
	v_pk_mul_f32 v[32:33], v[32:33], v[140:141]
	v_pk_mul_f32 v[28:29], v[28:29], v[128:129]
	v_pk_mul_f32 v[24:25], v[24:25], v[132:133]
	v_pk_mul_f32 v[20:21], v[20:21], v[136:137]
	v_pk_mul_f32 v[30:31], v[30:31], v[130:131]
	v_pk_mul_f32 v[26:27], v[26:27], v[134:135]
	v_pk_mul_f32 v[22:23], v[22:23], v[138:139]
	v_pk_mul_f32 v[18:19], v[18:19], v[142:143]
	v_pk_mul_f32 v[16:17], v[16:17], v[140:141]
; #define SBAR() __builtin_amdgcn_sched_barrier(0)
; template <int DK>
; __device__ __forceinline__ void partialSM(f32x16& p0, f32x16& p1, float& m_reg, float& mn, float& alpha) {
;     ...
;   float mnC = -mn * C;
; #pragma unroll
;   for (int r = 0; r < 16; ++r) p0[r] = fmaf(p0[r], C, mnC);
; #pragma unroll
;   for (int r = 0; r < 16; ++r) p1[r] = fmaf(p1[r], C, mnC);
; #pragma unroll
;   for (int r = 0; r < 16; ++r) p0[r] = __builtin_amdgcn_exp2f(p0[r]);
; }
; __device__ __forceinline__ void finishSM(f32x16& p0, f32x16& p1, float alpha, float& l_reg, bf16x8& pa0, bf16x8& pa1, bf16x8& pa2, bf16x8& pa3) {
; #pragma unroll
;   for (int r = 0; r < 16; ++r) p1[r] = __builtin_amdgcn_exp2f(p1[r]);
; template <int DK, int LDQ, int LDK, int LDV, int LDO, int SDEPTH, int NPARK>
; __device__ __forceinline__ void body(const bf16_t* __restrict__ Qb, const bf16_t* __restrict__ Kh, const bf16_t* __restrict__ Vh, bf16_t* __restrict__ Ob, int seq, char* lds, int tid, int wid) {
;     ...
;     SBAR(); qkt<DK, NPARK>(pA0, pA1, K_lds, qr, qpark, r32, hi);
;     finishSM(pB0, pB1, alB, l_reg, pa0, pa1, pa2, pa3); SBAR();
.LBB0_928:
	v_cndmask_b32_e64 v174, v144, v174, s[8:9]
	v_mul_f32_e32 v144, 0xbe0293ee, v174
	v_fmamk_f32 v80, v80, 0x3e0293ee, v144
	v_fmamk_f32 v81, v81, 0x3e0293ee, v144
	v_fmamk_f32 v82, v82, 0x3e0293ee, v144
	v_fmamk_f32 v83, v83, 0x3e0293ee, v144
	v_fmamk_f32 v84, v84, 0x3e0293ee, v144
	v_fmamk_f32 v85, v85, 0x3e0293ee, v144
	v_fmamk_f32 v86, v86, 0x3e0293ee, v144
	v_fmamk_f32 v87, v87, 0x3e0293ee, v144
	v_fmamk_f32 v88, v88, 0x3e0293ee, v144
	v_fmamk_f32 v89, v89, 0x3e0293ee, v144
	v_fmamk_f32 v90, v90, 0x3e0293ee, v144
	v_fmamk_f32 v91, v91, 0x3e0293ee, v144
	v_fmamk_f32 v92, v92, 0x3e0293ee, v144
	v_fmamk_f32 v93, v93, 0x3e0293ee, v144
	v_fmamk_f32 v94, v94, 0x3e0293ee, v144
	v_fmamk_f32 v95, v95, 0x3e0293ee, v144
	v_fmamk_f32 v184, v64, 0x3e0293ee, v144
	v_fmamk_f32 v185, v65, 0x3e0293ee, v144
	v_fmamk_f32 v186, v66, 0x3e0293ee, v144
	v_fmamk_f32 v187, v67, 0x3e0293ee, v144
	v_fmamk_f32 v188, v68, 0x3e0293ee, v144
	v_fmamk_f32 v146, v69, 0x3e0293ee, v144
	v_fmamk_f32 v147, v70, 0x3e0293ee, v144
	v_fmamk_f32 v179, v71, 0x3e0293ee, v144
	v_fmamk_f32 v180, v72, 0x3e0293ee, v144
	v_fmamk_f32 v181, v73, 0x3e0293ee, v144
	v_fmamk_f32 v182, v74, 0x3e0293ee, v144
	v_fmamk_f32 v183, v75, 0x3e0293ee, v144
	v_fmamk_f32 v145, v76, 0x3e0293ee, v144
	v_fmamk_f32 v189, v77, 0x3e0293ee, v144
	v_fmamk_f32 v190, v78, 0x3e0293ee, v144
	v_fmac_f32_e32 v144, 0x3e0293ee, v79
	v_exp_f32_e32 v141, v80
	v_exp_f32_e32 v143, v81
	v_exp_f32_e32 v139, v82
	v_exp_f32_e32 v142, v83
	v_exp_f32_e32 v138, v84
	v_exp_f32_e32 v140, v85
	v_exp_f32_e32 v136, v86
	v_exp_f32_e32 v137, v87
	v_exp_f32_e32 v133, v88
	v_exp_f32_e32 v135, v89
	v_exp_f32_e32 v132, v90
	v_exp_f32_e32 v134, v91
	v_exp_f32_e32 v129, v92
	v_exp_f32_e32 v131, v93
	v_exp_f32_e32 v128, v94
	v_exp_f32_e32 v130, v95
	s_waitcnt lgkmcnt(0)
	s_barrier
	ds_read_b128 v[64:67], v161 offset:32768
	ds_read_b128 v[68:71], v161 offset:40960
	ds_read_b128 v[194:197], v170 offset:32768
	ds_read_b128 v[198:201], v170 offset:40960
	v_exp_f32_e32 v203, v144
	v_add_f32_e32 v144, 0, v141
	s_waitcnt lgkmcnt(3)
	v_mfma_f32_32x32x16_bf16 v[80:95], v[64:67], v[112:115], 0
	v_add_f32_e32 v144, v143, v144
	v_add_f32_e32 v144, v139, v144
	v_add_f32_e32 v144, v142, v144
	v_add_f32_e32 v144, v138, v144
	v_add_f32_e32 v144, v140, v144
	v_add_f32_e32 v144, v136, v144
	v_add_f32_e32 v144, v137, v144
	s_waitcnt lgkmcnt(2)
	v_mfma_f32_32x32x16_bf16 v[64:79], v[68:71], v[112:115], 0
	v_add_f32_e32 v144, v133, v144
	v_add_f32_e32 v144, v135, v144
	v_add_f32_e32 v144, v132, v144
	v_add_f32_e32 v144, v134, v144
	v_exp_f32_e32 v191, v184
	v_add_f32_e32 v144, v129, v144
	v_exp_f32_e32 v185, v185
	s_waitcnt lgkmcnt(1)
	v_mfma_f32_32x32x16_bf16 v[80:95], v[194:197], v[108:111], v[80:95]
	v_add_f32_e32 v144, v131, v144
	v_add_f32_e32 v144, v128, v144
	v_add_f32_e32 v144, v130, v144
	v_add_f32_e32 v144, v191, v144
	v_add_f32_e32 v144, v185, v144
	v_exp_f32_e32 v179, v179
	v_exp_f32_e32 v180, v180
	s_waitcnt lgkmcnt(0)
	v_mfma_f32_32x32x16_bf16 v[64:79], v[198:201], v[108:111], v[64:79]
	ds_read_b128 v[194:197], v169 offset:32768
	ds_read_b128 v[198:201], v169 offset:40960
	v_exp_f32_e32 v181, v181
	v_exp_f32_e32 v182, v182
	v_exp_f32_e32 v202, v189
	v_exp_f32_e32 v190, v190
	s_waitcnt lgkmcnt(1)
	v_mfma_f32_32x32x16_bf16 v[80:95], v[194:197], v[120:123], v[80:95]
	s_waitcnt lgkmcnt(0)
	v_mfma_f32_32x32x16_bf16 v[64:79], v[198:201], v[120:123], v[64:79]
	ds_read_b128 v[194:197], v168 offset:32768
	ds_read_b128 v[198:201], v168 offset:40960
	s_waitcnt lgkmcnt(1)
	v_mfma_f32_32x32x16_bf16 v[80:95], v[194:197], v[124:127], v[80:95]
	s_waitcnt lgkmcnt(0)
	v_mfma_f32_32x32x16_bf16 v[64:79], v[198:201], v[124:127], v[64:79]
	ds_read_b128 v[194:197], v167 offset:32768
	ds_read_b128 v[198:201], v167 offset:40960
	s_waitcnt lgkmcnt(1)
	v_mfma_f32_32x32x16_bf16 v[80:95], v[194:197], v[116:119], v[80:95]
	s_waitcnt lgkmcnt(0)
	v_mfma_f32_32x32x16_bf16 v[64:79], v[198:201], v[116:119], v[64:79]
	ds_read_b128 v[194:197], v166 offset:32768
	ds_read_b128 v[198:201], v166 offset:40960
	s_waitcnt lgkmcnt(1)
	v_mfma_f32_32x32x16_bf16 v[80:95], v[194:197], v[104:107], v[80:95]
	s_waitcnt lgkmcnt(0)
	v_mfma_f32_32x32x16_bf16 v[64:79], v[198:201], v[104:107], v[64:79]
	ds_read_b128 v[194:197], v172 offset:32768
	ds_read_b128 v[198:201], v172 offset:40960
	s_waitcnt lgkmcnt(1)
	v_mfma_f32_32x32x16_bf16 v[80:95], v[194:197], v[100:103], v[80:95]
	s_waitcnt lgkmcnt(0)
	v_mfma_f32_32x32x16_bf16 v[64:79], v[198:201], v[100:103], v[64:79]
	ds_read_b128 v[194:197], v171 offset:32768
	ds_read_b128 v[198:201], v171 offset:40960
	s_waitcnt lgkmcnt(1)
	v_mfma_f32_32x32x16_bf16 v[80:95], v[194:197], v[96:99], v[80:95]
	v_exp_f32_e32 v195, v186
	v_exp_f32_e32 v196, v187
	v_exp_f32_e32 v197, v188
	v_add_f32_e32 v144, v195, v144
	v_add_f32_e32 v144, v196, v144
	v_add_f32_e32 v144, v197, v144
	s_waitcnt lgkmcnt(0)
; #define SBAR() __builtin_amdgcn_sched_barrier(0)
; __device__ __forceinline__ void finishSM(f32x16& p0, f32x16& p1, float alpha, float& l_reg, bf16x8& pa0, bf16x8& pa1, bf16x8& pa2, bf16x8& pa3) {
; #pragma unroll
;   for (int r = 0; r < 16; ++r) p1[r] = __builtin_amdgcn_exp2f(p1[r]);
;   float ps = 0;
; #pragma unroll
;   for (int r = 0; r < 16; ++r) ps += p0[r];
; #pragma unroll
;   for (int r = 0; r < 16; ++r) ps += p1[r];
;   { auto rr = __builtin_amdgcn_permlane32_swap(__float_as_uint(ps), __float_as_uint(ps), false, false);
;     ps = __uint_as_float(rr[0]) + __uint_as_float(rr[1]); }
;   l_reg = l_reg * alpha + ps;
;     ...
;   PK4(p0, 0, pa0); PK4(p0, 8, pa1); PK4(p1, 0, pa2); PK4(p1, 8, pa3);
;     ...
; }
; template <int D0> __device__ __forceinline__ void pv_one(f32x16& od, int vb, bf16x8 pa0, bf16x8 pa1, bf16x8 pa2, bf16x8 pa3) {
;   const s16x4 l0 = tr_read<v_rd_off(D0, 0, 0)>(vb), h0 = tr_read<v_rd_off(D0, 0, 1)>(vb), l1 = tr_read<v_rd_off(D0, 1, 0)>(vb), h1 = tr_read<v_rd_off(D0, 1, 1)>(vb);
;   const s16x4 l2 = tr_read<v_rd_off(D0, 2, 0)>(vb), h2 = tr_read<v_rd_off(D0, 2, 1)>(vb), l3 = tr_read<v_rd_off(D0, 3, 0)>(vb), h3 = tr_read<v_rd_off(D0, 3, 1)>(vb);
;   asm volatile("s_waitcnt lgkmcnt(0)" ::: "memory"); SBAR();
;     ...
;   od = __builtin_amdgcn_mfma_f32_32x32x16_bf16(pa0, PK(l0, h0), od, 0, 0, 0);
;   od = __builtin_amdgcn_mfma_f32_32x32x16_bf16(pa1, PK(l1, h1), od, 0, 0, 0);
;   od = __builtin_amdgcn_mfma_f32_32x32x16_bf16(pa2, PK(l2, h2), od, 0, 0, 0);
;   od = __builtin_amdgcn_mfma_f32_32x32x16_bf16(pa3, PK(l3, h3), od, 0, 0, 0);
;     ...
; }
; __device__ __forceinline__ void pv_d0(f32x16* o, int vb, bf16x8 pa0, bf16x8 pa1, bf16x8 pa2, bf16x8 pa3) {
;   pv_one<0>(o[0], vb, pa0, pa1, pa2, pa3); pv_one<1>(o[1], vb, pa0, pa1, pa2, pa3); pv_one<2>(o[2], vb, pa0, pa1, pa2, pa3); pv_one<3>(o[3], vb, pa0, pa1, pa2, pa3);
; template <int DK, int LDQ, int LDK, int LDV, int LDO, int SDEPTH, int NPARK>
; __device__ __forceinline__ void body(const bf16_t* __restrict__ Qb, const bf16_t* __restrict__ Kh, const bf16_t* __restrict__ Vh, bf16_t* __restrict__ Ob, int seq, char* lds, int tid, int wid) {
;     ...
;     if (SDEPTH == 1 || j + 3 < NT) SLOAD(SE, (j + 1 + SDEPTH) * KVBLK); SBAR();
;     pv_d0(o, vb0 + (int)SHM_V, pa0, pa1, pa2, pa3); partialSM<DK>(pA0, pA1, m_reg, mnA, alA);
	v_mfma_f32_32x32x16_bf16 v[64:79], v[198:201], v[96:99], v[64:79]
	v_exp_f32_e32 v198, v146
	v_exp_f32_e32 v199, v147
	v_exp_f32_e32 v200, v183
	v_exp_f32_e32 v201, v145
	v_add_f32_e32 v144, v198, v144
	v_add_f32_e32 v144, v199, v144
	v_add_f32_e32 v144, v179, v144
	v_add_f32_e32 v144, v180, v144
	v_add_f32_e32 v144, v181, v144
	v_add_f32_e32 v144, v182, v144
	v_add_f32_e32 v144, v200, v144
	v_add_f32_e32 v144, v201, v144
	v_add_f32_e32 v144, v202, v144
	v_add_f32_e32 v144, v190, v144
	v_add_f32_e32 v183, v203, v144
	v_mov_b32_e32 v184, v183
	v_cvt_pk_bf16_f32 v144, v141, v143
	v_cvt_pk_bf16_f32 v145, v139, v142
	v_cvt_pk_bf16_f32 v146, v138, v140
	v_cvt_pk_bf16_f32 v147, v136, v137
	s_nop 1
	v_permlane32_swap_b32_e32 v183, v184
	v_permlane32_swap_b32_e32 v144, v146
	v_permlane32_swap_b32_e32 v145, v147
	v_cvt_pk_bf16_f32 v186, v133, v135
	v_cvt_pk_bf16_f32 v187, v132, v134
	v_cvt_pk_bf16_f32 v188, v129, v131
	v_cvt_pk_bf16_f32 v189, v128, v130
	v_cvt_pk_bf16_f32 v194, v191, v185
	v_cvt_pk_bf16_f32 v195, v195, v196
	v_cvt_pk_bf16_f32 v196, v197, v198
	v_cvt_pk_bf16_f32 v197, v199, v179
	v_cvt_pk_bf16_f32 v198, v180, v181
	v_cvt_pk_bf16_f32 v199, v182, v200
	v_cvt_pk_bf16_f32 v200, v201, v202
	v_cvt_pk_bf16_f32 v201, v190, v203
	s_nop 0
	v_permlane32_swap_b32_e32 v186, v188
	v_permlane32_swap_b32_e32 v187, v189
	v_permlane32_swap_b32_e32 v194, v196
	v_permlane32_swap_b32_e32 v195, v197
	v_permlane32_swap_b32_e32 v198, v200
	v_permlane32_swap_b32_e32 v199, v201
	s_add_u32 s46, s10, s61
	s_addc_u32 s47, s11, 0
	s_add_u32 s48, s10, s64
	s_addc_u32 s49, s11, 0
	global_load_dwordx4 v[128:131], v192, s[46:47]
	global_load_dwordx4 v[132:135], v152, s[46:47]
	global_load_dwordx4 v[136:139], v192, s[48:49]
	global_load_dwordx4 v[140:143], v152, s[48:49]
	ds_read_b64_tr_b16 v[154:155], v159 offset:0
	ds_read_b64_tr_b16 v[156:157], v159 offset:0x800
	ds_read_b64_tr_b16 v[202:203], v159 offset:0x1000
	ds_read_b64_tr_b16 v[204:205], v159 offset:0x1800
	ds_read_b64_tr_b16 v[206:207], v159 offset:0x2000
	ds_read_b64_tr_b16 v[208:209], v159 offset:0x2800
	ds_read_b64_tr_b16 v[210:211], v159 offset:0x3000
	ds_read_b64_tr_b16 v[212:213], v159 offset:0x3800
	s_waitcnt lgkmcnt(0)
	s_nop 0
	v_mfma_f32_32x32x16_bf16 v[0:15], v[144:147], v[154:157], v[0:15]
	ds_read_b64_tr_b16 v[154:155], v159 offset:0x200
	ds_read_b64_tr_b16 v[156:157], v159 offset:0xa00
	v_mfma_f32_32x32x16_bf16 v[0:15], v[186:189], v[202:205], v[0:15]
	ds_read_b64_tr_b16 v[202:203], v159 offset:0x1200
	ds_read_b64_tr_b16 v[204:205], v159 offset:0x1a00
	v_mfma_f32_32x32x16_bf16 v[0:15], v[194:197], v[206:209], v[0:15]
	ds_read_b64_tr_b16 v[206:207], v159 offset:0x2200
	ds_read_b64_tr_b16 v[208:209], v159 offset:0x2a00
	v_mfma_f32_32x32x16_bf16 v[0:15], v[198:201], v[210:213], v[0:15]
	ds_read_b64_tr_b16 v[210:211], v159 offset:0x3200
	ds_read_b64_tr_b16 v[212:213], v159 offset:0x3a00
	s_waitcnt lgkmcnt(0)
	v_mfma_f32_32x32x16_bf16 v[48:63], v[144:147], v[154:157], v[48:63]
	ds_read_b64_tr_b16 v[154:155], v159 offset:0x400
	ds_read_b64_tr_b16 v[156:157], v159 offset:0xc00
	v_mfma_f32_32x32x16_bf16 v[48:63], v[186:189], v[202:205], v[48:63]
	ds_read_b64_tr_b16 v[202:203], v159 offset:0x1400
	ds_read_b64_tr_b16 v[204:205], v159 offset:0x1c00
	v_mfma_f32_32x32x16_bf16 v[48:63], v[194:197], v[206:209], v[48:63]
	ds_read_b64_tr_b16 v[206:207], v159 offset:0x2400
	ds_read_b64_tr_b16 v[208:209], v159 offset:0x2c00
	v_mfma_f32_32x32x16_bf16 v[48:63], v[198:201], v[210:213], v[48:63]
	ds_read_b64_tr_b16 v[210:211], v159 offset:0x3400
	ds_read_b64_tr_b16 v[212:213], v159 offset:0x3c00
	s_waitcnt lgkmcnt(0)
	v_mfma_f32_32x32x16_bf16 v[32:47], v[144:147], v[154:157], v[32:47]
	ds_read_b64_tr_b16 v[154:155], v159 offset:0x600
	ds_read_b64_tr_b16 v[156:157], v159 offset:0xe00
	v_mfma_f32_32x32x16_bf16 v[32:47], v[186:189], v[202:205], v[32:47]
	ds_read_b64_tr_b16 v[202:203], v159 offset:0x1600
	ds_read_b64_tr_b16 v[204:205], v159 offset:0x1e00
	v_mfma_f32_32x32x16_bf16 v[32:47], v[194:197], v[206:209], v[32:47]
	ds_read_b64_tr_b16 v[206:207], v159 offset:0x2600
	ds_read_b64_tr_b16 v[208:209], v159 offset:0x2e00
	v_mfma_f32_32x32x16_bf16 v[32:47], v[198:201], v[210:213], v[32:47]
	ds_read_b64_tr_b16 v[210:211], v159 offset:0x3600
	ds_read_b64_tr_b16 v[212:213], v159 offset:0x3e00
	s_waitcnt lgkmcnt(0)
	v_mfma_f32_32x32x16_bf16 v[16:31], v[144:147], v[154:157], v[16:31]
	v_max_f32_e32 v144, v81, v81
	v_max_f32_e32 v145, v80, v80
	v_max_f32_e32 v144, v145, v144
	v_max3_f32 v144, v144, v82, v83
	v_max3_f32 v144, v144, v84, v85
	v_max3_f32 v144, v144, v86, v87
	v_max3_f32 v144, v144, v88, v89
	v_max3_f32 v144, v144, v90, v91
	v_max3_f32 v144, v144, v92, v93
	v_mfma_f32_32x32x16_bf16 v[16:31], v[186:189], v[202:205], v[16:31]
	v_max3_f32 v144, v144, v94, v95
	v_max3_f32 v144, v144, v64, v65
	v_max3_f32 v144, v144, v66, v67
	v_max3_f32 v144, v144, v68, v69
	v_max3_f32 v144, v144, v70, v71
	v_max3_f32 v144, v144, v72, v73
	v_max3_f32 v144, v144, v74, v75
	v_max3_f32 v144, v144, v76, v77
	v_mfma_f32_32x32x16_bf16 v[16:31], v[194:197], v[206:209], v[16:31]
	v_max3_f32 v144, v144, v78, v79
	v_mov_b32_e32 v145, v144
	s_nop 1
	v_permlane32_swap_b32_e32 v144, v145
	v_max_f32_e32 v145, v145, v145
	v_max_f32_e32 v144, v144, v144
	v_max_f32_e32 v144, v144, v145
	v_sub_f32_e32 v145, v144, v174
	v_cmp_ge_f32_e32 vcc, s1, v145
	v_max_f32_e32 v145, v174, v174
	v_max_f32_e32 v145, v145, v144
	v_mfma_f32_32x32x16_bf16 v[16:31], v[198:201], v[210:213], v[16:31]
	v_sub_f32_e32 v144, v174, v145
	v_mul_f32_e32 v144, 0x3e0293ee, v144
	v_exp_f32_e32 v144, v144
	s_cmp_eq_u64 vcc, exec
	s_cselect_b64 s[8:9], -1, 0
	s_barrier
; #define SWAIT() do { if constexpr (SDEPTH == 2) { if constexpr (DK == 192) asm volatile("s_waitcnt vmcnt(5)" ::: "memory"); else asm volatile("s_waitcnt vmcnt(4)" ::: "memory"); } else asm volatile("s_waitcnt vmcnt(0)" ::: "memory"); } while (0)
; #define RESC(a) do { if (__any((a) < 1.f)) { if (hi == 0) al_l[r32] = (a); asm volatile("s_waitcnt lgkmcnt(0)" ::: "memory"); \
;     _Pragma("unroll") for (int d = 0; d < 4; ++d) _Pragma("unroll") for (int r = 0; r < 16; ++r) o[d][r] *= al_l[crow(r, hi)]; } } while (0)
; template <int DK, int LDQ, int LDK, int LDV, int LDO, int SDEPTH, int NPARK>
; __device__ __forceinline__ void body(const bf16_t* __restrict__ Qb, const bf16_t* __restrict__ Kh, const bf16_t* __restrict__ Vh, bf16_t* __restrict__ Ob, int seq, char* lds, int tid, int wid) {
;     ...
;     __syncthreads(); SWAIT(); SWRITE(1, SO);
;     RESC(alA); __syncthreads();
	s_waitcnt vmcnt(0)
	v_cndmask_b32_e64 v144, v144, 1.0, s[8:9]
	v_cmp_gt_f32_e32 vcc, 1.0, v144
	s_waitcnt vmcnt(3)
	ds_write_b128 v164, v[128:131] offset:16384
	s_waitcnt vmcnt(2)
	ds_write_b128 v165, v[132:135] offset:16384
	s_waitcnt vmcnt(1)
	ds_write_b128 v162, v[136:139] offset:49152
	s_waitcnt vmcnt(0)
	ds_write_b128 v163, v[140:143] offset:49152
	s_cbranch_vccz .LBB0_932
	s_and_saveexec_b64 s[12:13], s[6:7]
	ds_write_b32 v151, v144 offset:128
	s_or_b64 exec, exec, s[12:13]
	s_waitcnt lgkmcnt(0)
	v_add_u32_e32 v140, s95, v150
	ds_read_b128 v[128:131], v140 offset:224
	ds_read_b128 v[132:135], v140 offset:192
	ds_read_b128 v[136:139], v140 offset:160
	ds_read_b128 v[140:143], v140 offset:128
	s_waitcnt lgkmcnt(3)
	v_pk_mul_f32 v[12:13], v[12:13], v[128:129]
	s_waitcnt lgkmcnt(2)
	v_pk_mul_f32 v[8:9], v[8:9], v[132:133]
	s_waitcnt lgkmcnt(1)
	v_pk_mul_f32 v[4:5], v[4:5], v[136:137]
	v_pk_mul_f32 v[14:15], v[14:15], v[130:131]
	v_pk_mul_f32 v[10:11], v[10:11], v[134:135]
	v_pk_mul_f32 v[6:7], v[6:7], v[138:139]
	s_waitcnt lgkmcnt(0)
	v_pk_mul_f32 v[2:3], v[2:3], v[142:143]
	v_pk_mul_f32 v[0:1], v[0:1], v[140:141]
	v_pk_mul_f32 v[60:61], v[60:61], v[128:129]
	v_pk_mul_f32 v[56:57], v[56:57], v[132:133]
	v_pk_mul_f32 v[52:53], v[52:53], v[136:137]
	v_pk_mul_f32 v[62:63], v[62:63], v[130:131]
	v_pk_mul_f32 v[58:59], v[58:59], v[134:135]
	v_pk_mul_f32 v[54:55], v[54:55], v[138:139]
	v_pk_mul_f32 v[50:51], v[50:51], v[142:143]
	v_pk_mul_f32 v[48:49], v[48:49], v[140:141]
	v_pk_mul_f32 v[44:45], v[44:45], v[128:129]
	v_pk_mul_f32 v[40:41], v[40:41], v[132:133]
	v_pk_mul_f32 v[36:37], v[36:37], v[136:137]
	v_pk_mul_f32 v[46:47], v[46:47], v[130:131]
	v_pk_mul_f32 v[42:43], v[42:43], v[134:135]
	v_pk_mul_f32 v[38:39], v[38:39], v[138:139]
	v_pk_mul_f32 v[34:35], v[34:35], v[142:143]
	v_pk_mul_f32 v[32:33], v[32:33], v[140:141]
	v_pk_mul_f32 v[28:29], v[28:29], v[128:129]
	v_pk_mul_f32 v[24:25], v[24:25], v[132:133]
	v_pk_mul_f32 v[20:21], v[20:21], v[136:137]
	v_pk_mul_f32 v[30:31], v[30:31], v[130:131]
	v_pk_mul_f32 v[26:27], v[26:27], v[134:135]
	v_pk_mul_f32 v[22:23], v[22:23], v[138:139]
	v_pk_mul_f32 v[18:19], v[18:19], v[142:143]
	v_pk_mul_f32 v[16:17], v[16:17], v[140:141]
